# layer-1 in-projection: the 64 tiles of the 11th round (xq1 columns, consumed 3 phases later) deferred past the grid barrier to workgroups 448-511 which have a spare slot in the HGRN chunk phase
# baseline (speedup 1.0000x reference)
; DI float siluf_(float x) { return x * __builtin_amdgcn_rcpf(1.f + __expf(-x)); }
; template <class AL, class BL, class EP>
; DI void gemm_phase(int MT, int NTL, int K, AL al, BL bl, EP ep, char* smem) {
;   for (int t = blockIdx.x; t < MT * NTL; t += gridDim.x) {
;     const int tm = t % MT, tn = t / MT;
;     f32x16 acc[2][2];
;     gemm_core(al, bl, tm * 128, tn * 128, K, smem, acc);
;     ep(acc, tm * 128, tn * 128);
;   }
; __global__ void __launch_bounds__(256, 2) fwd_megakernel(Params p) {
;     ...
;     gemm_phase(NT / 128, 36, 1024,
;                [=](int m, int k) { return xb1 + (long)m * XR_LD + k; },
;                [=](int n, int k) { return win1T + (long)n * 1024 + k; },
;                [=](const f32x16 (&acc)[2][2], int m0, int n0) {
;                  const int cb = n0 >> 10;
;                  if (cb == 0) epi_bf16_tile(acc, m0, n0, qs + (long)m0 * 1024 + n0, 1024, smem, [=](int m, int n, float v) { return siluf_(v * rs[m]); });
;                  else if (cb == 1) epi_each(acc, m0, n0, [=](int m, int n, float v) { f[(long)m * 1024 + (n - 1024)] = v * rs[m]; });
;                  else if (cb == 2) epi_bf16_tile(acc, m0, n0, vv + (long)m0 * 1024 + (n0 - 2048), 1024, smem, [=](int m, int n, float v) { return v * rs[m]; });
;                  else if (cb == 3) epi_bf16_tile(acc, m0, n0, gs + (long)m0 * 1024 + (n0 - 3072), 1024, smem, [=](int m, int n, float v) { return siluf_(v * rs[m]); });
;                  else epi_bf16_tile(acc, m0, n0, xq1 + (long)m0 * 512 + (n0 - 4096), 512, smem, [=](int m, int n, float v) { return v * rs[m] * XSCALE; });
;                }, smem);
.LBB0_1188:
	s_or_b64 exec, exec, s[0:1]
	s_cmpk_gt_i32 s78, 0x143f
	s_mov_b64 s[2:3], s[70:71]
	s_waitcnt lgkmcnt(0)
	s_barrier
	s_mov_b32 s99, 0
	s_cbranch_scc1 .LBB0_1210
.Lx12_pre:
	s_add_u32 s12, s70, 0x12400000
	s_addc_u32 s13, s71, 0
	s_add_u32 s33, s70, 0x400000
	s_addc_u32 s38, s71, 0
	s_add_u32 s14, s70, 0x2800000
	s_addc_u32 s15, s71, 0
	s_add_u32 s18, s70, 0x10000
	s_mov_b64 s[16:17], 0x10000
	s_addc_u32 s19, s71, 0
	s_add_i32 s39, s67, 48
	s_mul_i32 s98, s99, 0x92000
	s_add_i32 s39, s39, s98
	s_lshl_b32 s40, s50, 7
	v_mov_b32_e32 v85, 0
	s_mov_b32 s41, 0x10000
	s_mov_b32 s21, 0
	s_mov_b64 s[22:23], 0x20000
	s_mov_b32 s42, 0x20000
	s_mov_b64 s[24:25], 0x30000
	s_mov_b32 s43, 0x30000
	s_movk_i32 s44, 0x90
	s_mov_b32 s45, 0xfffffc0
	s_movk_i32 s46, 0xffc0
	s_movk_i32 s47, 0x110
	s_mov_b64 s[26:27], 0x93fe800
	s_mov_b64 s[28:29], 0x6fff000
	s_mov_b64 s[30:31], 0xb7fe000
	s_mul_i32 s98, s99, 0x1240
	s_add_i32 s51, s78, s98
	s_movk_i32 s100, 0x1440
	s_cmpk_eq_u32 s50, 0x200
	s_cselect_b32 s100, 0x1400, s100
	s_branch .LBB0_1191
.LBB0_1190:
	s_add_i32 s51, s51, s50
	s_add_i32 s39, s39, s40
	s_cmp_lt_i32 s51, s100
	s_cbranch_scc0 .LBB0_1209

; DI unsigned xb_ld(unsigned* p) { return __hip_atomic_load(p, __ATOMIC_RELAXED, __HIP_MEMORY_SCOPE_AGENT); }
; DI unsigned xb_add(unsigned* p, unsigned v) { return __hip_atomic_fetch_add(p, v, __ATOMIC_RELAXED, __HIP_MEMORY_SCOPE_AGENT); }
; #define XB_SPIN(cond, bar) do { unsigned _sp = 0; while (cond) { __builtin_amdgcn_s_sleep(1); \
;     if ((++_sp & 255u) == 0u) { if (xb_ld(&(bar)[XB_TMO])) break; if (_sp > XB_SPIN_CAP) { atomicAdd(&(bar)[XB_TMO], 1u); break; } } } } while (0)
; DI void xcd_barrier(const XcdBarrier& b) {
;   asm volatile("s_waitcnt vmcnt(0)" ::: "memory");
;   __syncthreads();
;   if (threadIdx.x == 0) {
;     unsigned* bar = b.bar;
;     __builtin_amdgcn_s_waitcnt(0);
;     unsigned nloc = b.st[0], nx = b.st[1];
;     if (nloc == 0u) { xcd_barrier_complete(bar, b.x, nloc, nx); b.st[0] = nloc; b.st[1] = nx; }
;     const unsigned old = xb_add(&bar[XB_XSUB(b.x)], 1u);
;     const unsigned gen = old / nloc;
;     if (old + 1u == (gen + 1u) * nloc) {
;       __builtin_amdgcn_fence(__ATOMIC_RELEASE, "agent");
;       asm volatile("s_waitcnt vmcnt(0)" ::: "memory");
;       const unsigned og = xb_add(&bar[XB_TOP], 1u);
;       const unsigned tg = og / nx;
;       if (og + 1u == (tg + 1u) * nx) xb_add(&bar[XB_TOPGEN], 1u);
;       else XB_SPIN(xb_ld(&bar[XB_TOPGEN]) == tg, bar);
;       __builtin_amdgcn_fence(__ATOMIC_ACQUIRE, "agent");
;       xb_add(&bar[XB_XGEN(b.x)], 1u);
;       asm volatile("s_waitcnt vmcnt(0)" ::: "memory");
;     } else {
;       XB_SPIN(xb_ld(&bar[XB_XGEN(b.x)]) == gen, bar);
;       __builtin_amdgcn_fence(__ATOMIC_ACQUIRE, "agent");
;       asm volatile("s_waitcnt vmcnt(0)" ::: "memory");
;     }
;   }
;   __syncthreads();
; }
.LBB0_1210:
	s_cmp_lg_u32 s99, 0
	s_cbranch_scc1 .Lx12_back
	s_getreg_b32 s12, hwreg(HW_REG_XCC_ID, 0, 4)
	s_waitcnt vmcnt(0)
	s_barrier
	s_and_saveexec_b64 s[0:1], s[4:5]
	s_cbranch_execz .LBB0_1262
	v_readlane_b32 s98, v226, 47
	v_readlane_b32 s99, v226, 48
	v_readlane_b32 s101, v226, 49
	v_readlane_b32 s100, v226, 46
	v_readlane_b32 vcc_hi, v226, 50
	s_getreg_b32 vcc_lo, hwreg(HW_REG_XCC_ID, 0, 4)
	s_add_u32 s100, s100, 1
	s_lshl_b32 vcc_lo, vcc_lo, 8
	v_writelane_b32 v226, s100, 46
	s_add_u32 vcc_lo, vcc_lo, 0x1400
	s_mul_i32 s101, s101, s100
	s_mul_i32 s100, vcc_hi, s100
	v_mov_b32_e32 v253, vcc_lo
	v_mov_b32_e32 v254, 1
	global_atomic_add v254, v253, v254, s[98:99] sc0
	v_add_u32_e32 v253, 0x1000, v253
	s_waitcnt vmcnt(0)
	v_readfirstlane_b32 vcc_lo, v254
	s_add_u32 vcc_lo, vcc_lo, 1
	s_cmp_lg_u32 vcc_lo, s100
	s_cbranch_scc1 .Lfb_poll_10
	buffer_wbl2 sc1
	s_waitcnt vmcnt(0)
	s_mov_b64 exec, 0xffff
	v_mbcnt_lo_u32_b32 v255, -1, 0
	v_mov_b32_e32 v254, vcc_hi
	v_lshlrev_b32_e32 v255, 8, v255
	v_add_u32_e32 v255, 0x2400, v255
	global_atomic_add v255, v254, s[98:99]
	s_mov_b64 exec, 1

; DI int opaque_tid() { int t = threadIdx.x; asm volatile("" : "+v"(t)); return t; }
; #define GRID_BARRIER() do { XcdBarrier b_; b_.bar = (unsigned*)p.ws; b_.x = xb_xcc_id(); b_.st = (volatile LAS unsigned*)(smem + SMEM_MAIN); xcd_barrier(b_); } while (0)
; DI void hgrn_chunk_item(const Params& p, int n, int hd, char* smem) {
;   char* ws = launder(p.ws);
;   u16* qs = (u16*)(ws + W_QS);
;   float* f = (float*)(ws + W_F);
;   const u16* vv = (const u16*)(ws + W_V);
;   u16* U = (u16*)(ws + W_U);
;   float* decay = (float*)(ws + W_DECAY);
;   const float* lbv = (const float*)(ws + W_LBV);
;   u16* QS = (u16*)smem;
;   u16* KS = QS + 64 * 136;
;   u16* KDT = KS + 64 * 136;
;   u16* VTs = KDT + 128 * 68;
;   float* tot = (float*)(VTs + 128 * 68);
;   float* lg32 = tot + 256;
;   const int tid = opaque_tid(), lane = tid & 63, w = tid >> 6, h = lane >> 5, r = lane & 31;
;   const int d = tid & 127, hf = tid >> 7;
;   const long t0 = (n < 256) ? (long)n * 64 : (long)NP + (long)(n - 256) * 64;
;   const int col = hd * 128 + d;
;   const float lb = lbv[col];
; __global__ void __launch_bounds__(256, 2) fwd_megakernel(Params p) {
;     ...
;   GRID_BARRIER();
;   for (int it = blockIdx.x; it < NCHUNK * 8; it += gridDim.x) hgrn_chunk_item(p, it >> 3, it & 7, smem);
.LBB0_1262:
	s_or_b64 exec, exec, s[0:1]
	s_cmpk_eq_u32 s50, 0x200
	s_cbranch_scc0 .Lx12_skip
	s_cmpk_lt_u32 s78, 0x1c0
	s_cbranch_scc1 .Lx12_skip
	s_mov_b32 s99, 1
	s_branch .Lx12_pre
.Lx12_back:
	s_mov_b32 s99, 0
.Lx12_skip:
	s_cmpk_lt_i32 s78, 0x900
	s_cselect_b64 s[16:17], -1, 0
	s_cmpk_gt_i32 s78, 0x8ff
	s_waitcnt lgkmcnt(0)
	s_barrier
	s_cbranch_scc1 .LBB0_1281
	s_add_u32 s18, s48, 0x2800000
	s_addc_u32 s19, s49, 0
	s_add_u32 s33, s48, 0x40000
	s_addc_u32 s34, s49, 0
	s_add_u32 s20, s48, 0x31000
	s_addc_u32 s21, s49, 0
	s_add_u32 s35, s48, 0xca00000
	s_addc_u32 s36, s49, 0
	s_mov_b32 s23, 0
	s_mov_b64 s[24:25], 0x4000
	s_waitcnt vmcnt(8)
	v_mov_b32_e32 v81, 0
	v_mov_b32_e32 v82, 0x11400
	s_movk_i32 s37, 0x1000
	s_mov_b32 s38, 0x800000
	s_mov_b32 s39, 0x3f317217
	s_mov_b32 s40, 0x7f800000
	v_mov_b32_e32 v83, 0x41b17218
	v_mov_b32_e32 v84, 0x11000
	s_movk_i32 s41, 0x80
	s_mov_b32 s42, 0x8800
	s_movk_i32 s43, 0x2200
	s_mov_b32 s44, 0x400000
	s_mov_b32 s45, 0x401000
	s_mov_b32 s46, 0x402000
	s_mov_b32 s47, 0x403000
	s_mov_b64 s[26:27], 0x8000
	s_movk_i32 s51, 0x110
	s_movk_i32 s52, 0x88
	s_mov_b32 s53, s78
	s_mov_b32 s54, s78
	s_branch .LBB0_1265
